# K-loops: LDS-DMA loads (with their m0/SALU setup) issued at the head of each load segment, before the ds_reads
# baseline (speedup 1.0000x reference)
.LBB0_453:
	s_add_u32 s24, s22, 0xfffc0080
	s_addc_u32 s25, s23, -1
	s_add_i32 s76, 0, 0x10000
	s_cmp_eq_u32 vcc_lo, 12
	s_cselect_b32 s29, s30, s25
	s_cselect_b32 s28, s31, s24
	s_cselect_b32 s25, s69, s99
	s_cselect_b32 s24, s75, s81
	s_add_i32 vcc_hi, 0, 0x14000
	s_add_i32 m0, s57, 0xc000
	s_nop 0
	global_load_lds_dwordx4 v194, s[22:23]
	s_add_i32 m0, s57, 0xe000
	s_nop 0
	global_load_lds_dwordx4 v196, s[22:23]
	v_add_u32_e32 v114, s76, v220
	ds_read_b128 v[106:109], v114
	ds_read_b128 v[110:113], v114 offset:1024
	ds_read_b128 v[128:131], v114 offset:2048
	ds_read_b128 v[132:135], v114 offset:3072
	v_add_u32_e32 v114, vcc_hi, v220
	ds_read_b128 v[136:139], v114
	ds_read_b128 v[158:161], v114 offset:1024
	ds_read_b128 v[162:165], v114 offset:2048
	ds_read_b128 v[166:169], v114 offset:3072
	ds_read_b128 v[170:173], v234
	ds_read_b128 v[174:177], v234 offset:1024
	ds_read_b128 v[178:181], v234 offset:2048
	ds_read_b128 v[198:201], v234 offset:3072
	ds_read_b128 v[202:205], v234 offset:4096
	ds_read_b128 v[206:209], v234 offset:5120
	ds_read_b128 v[210:213], v234 offset:6144
	ds_read_b128 v[214:217], v234 offset:7168
	s_waitcnt vmcnt(8)
	s_waitcnt lgkmcnt(0)
	s_barrier
	s_setprio 1
	v_mfma_f32_16x16x32_bf16 v[124:127], v[106:109], v[170:173], v[124:127]
	v_mfma_f32_16x16x32_bf16 v[98:101], v[128:131], v[170:173], v[98:101]
	v_mfma_f32_16x16x32_bf16 v[154:157], v[106:109], v[178:181], v[154:157]
	v_mfma_f32_16x16x32_bf16 v[58:61], v[128:131], v[178:181], v[58:61]
	v_mfma_f32_16x16x32_bf16 v[146:149], v[106:109], v[202:205], v[146:149]
	v_mfma_f32_16x16x32_bf16 v[46:49], v[128:131], v[202:205], v[46:49]
	v_mfma_f32_16x16x32_bf16 v[102:105], v[106:109], v[210:213], v[102:105]
	v_mfma_f32_16x16x32_bf16 v[54:57], v[128:131], v[210:213], v[54:57]
	v_mfma_f32_16x16x32_bf16 v[124:127], v[110:113], v[174:177], v[124:127]
	v_mfma_f32_16x16x32_bf16 v[98:101], v[132:135], v[174:177], v[98:101]
	v_mfma_f32_16x16x32_bf16 v[154:157], v[110:113], v[198:201], v[154:157]
	v_mfma_f32_16x16x32_bf16 v[58:61], v[132:135], v[198:201], v[58:61]
	v_mfma_f32_16x16x32_bf16 v[146:149], v[110:113], v[206:209], v[146:149]
	v_mfma_f32_16x16x32_bf16 v[46:49], v[132:135], v[206:209], v[46:49]
	v_mfma_f32_16x16x32_bf16 v[102:105], v[110:113], v[214:217], v[102:105]
	v_mfma_f32_16x16x32_bf16 v[54:57], v[132:135], v[214:217], v[54:57]
	v_mfma_f32_16x16x32_bf16 v[120:123], v[136:139], v[170:173], v[120:123]
	v_mfma_f32_16x16x32_bf16 v[94:97], v[162:165], v[170:173], v[94:97]
	v_mfma_f32_16x16x32_bf16 v[150:153], v[136:139], v[178:181], v[150:153]
	v_mfma_f32_16x16x32_bf16 v[50:53], v[162:165], v[178:181], v[50:53]
	v_mfma_f32_16x16x32_bf16 v[140:143], v[136:139], v[202:205], v[142:145]
	v_mfma_f32_16x16x32_bf16 v[42:45], v[162:165], v[202:205], v[42:45]
	v_mfma_f32_16x16x32_bf16 v[114:117], v[136:139], v[210:213], v[116:119]
	v_mfma_f32_16x16x32_bf16 v[38:41], v[162:165], v[210:213], v[38:41]
	v_mfma_f32_16x16x32_bf16 v[120:123], v[158:161], v[174:177], v[120:123]
	v_mfma_f32_16x16x32_bf16 v[94:97], v[166:169], v[174:177], v[94:97]
	v_mfma_f32_16x16x32_bf16 v[150:153], v[158:161], v[198:201], v[150:153]
	v_mfma_f32_16x16x32_bf16 v[50:53], v[166:169], v[198:201], v[50:53]
	v_mfma_f32_16x16x32_bf16 v[140:143], v[158:161], v[206:209], v[140:143]
	v_mfma_f32_16x16x32_bf16 v[42:45], v[166:169], v[206:209], v[42:45]
	v_mfma_f32_16x16x32_bf16 v[114:117], v[158:161], v[214:217], v[114:117]
	v_mfma_f32_16x16x32_bf16 v[38:41], v[166:169], v[214:217], v[38:41]
	s_setprio 0
	s_barrier
	s_add_i32 s76, s76, s42
	s_mov_b32 m0, s76
	s_nop 0
	global_load_lds_dwordx4 v0, s[24:25]
	s_add_i32 m0, s76, 0x2000
	s_add_u32 s76, s24, 0x40000
	s_addc_u32 s77, s25, 0
	s_add_i32 vcc_hi, vcc_hi, s42
	global_load_lds_dwordx4 v192, s[24:25]
	s_mov_b32 m0, vcc_hi
	s_nop 0
	global_load_lds_dwordx4 v0, s[76:77]
	s_add_i32 m0, vcc_hi, 0x2000
	s_nop 0
	global_load_lds_dwordx4 v192, s[76:77]
	s_mov_b32 m0, s57
	s_nop 0
	global_load_lds_dwordx4 v188, s[28:29]
	s_mov_b32 m0, s66
	s_nop 0
	global_load_lds_dwordx4 v190, s[28:29]
	ds_read_b128 v[170:173], v234 offset:16384
	ds_read_b128 v[174:177], v234 offset:17408
	ds_read_b128 v[178:181], v234 offset:18432
	ds_read_b128 v[198:201], v234 offset:19456
	ds_read_b128 v[202:205], v234 offset:20480
	ds_read_b128 v[206:209], v234 offset:21504
	ds_read_b128 v[210:213], v234 offset:22528
	ds_read_b128 v[214:217], v234 offset:23552
	s_waitcnt vmcnt(8)
	s_waitcnt lgkmcnt(0)
	s_barrier
	s_setprio 1
	v_mfma_f32_16x16x32_bf16 v[86:89], v[106:109], v[170:173], v[86:89]
	v_mfma_f32_16x16x32_bf16 v[30:33], v[128:131], v[170:173], v[30:33]
	v_mfma_f32_16x16x32_bf16 v[78:81], v[106:109], v[178:181], v[78:81]
	v_mfma_f32_16x16x32_bf16 v[22:25], v[128:131], v[178:181], v[22:25]
	v_mfma_f32_16x16x32_bf16 v[70:73], v[106:109], v[202:205], v[70:73]
	v_mfma_f32_16x16x32_bf16 v[14:17], v[128:131], v[202:205], v[14:17]
	v_mfma_f32_16x16x32_bf16 v[90:93], v[106:109], v[210:213], v[90:93]
	v_mfma_f32_16x16x32_bf16 v[34:37], v[128:131], v[210:213], v[34:37]
	v_mfma_f32_16x16x32_bf16 v[86:89], v[110:113], v[174:177], v[86:89]
	v_mfma_f32_16x16x32_bf16 v[30:33], v[132:135], v[174:177], v[30:33]
	v_mfma_f32_16x16x32_bf16 v[78:81], v[110:113], v[198:201], v[78:81]
	v_mfma_f32_16x16x32_bf16 v[22:25], v[132:135], v[198:201], v[22:25]
	v_mfma_f32_16x16x32_bf16 v[70:73], v[110:113], v[206:209], v[70:73]
	v_mfma_f32_16x16x32_bf16 v[14:17], v[132:135], v[206:209], v[14:17]
	v_mfma_f32_16x16x32_bf16 v[90:93], v[110:113], v[214:217], v[90:93]
	v_mfma_f32_16x16x32_bf16 v[34:37], v[132:135], v[214:217], v[34:37]
	v_mfma_f32_16x16x32_bf16 v[82:85], v[136:139], v[170:173], v[82:85]
	v_mfma_f32_16x16x32_bf16 v[26:29], v[162:165], v[170:173], v[26:29]
	v_mfma_f32_16x16x32_bf16 v[74:77], v[136:139], v[178:181], v[74:77]
	v_mfma_f32_16x16x32_bf16 v[18:21], v[162:165], v[178:181], v[18:21]
	v_mfma_f32_16x16x32_bf16 v[66:69], v[136:139], v[202:205], v[66:69]
	v_mfma_f32_16x16x32_bf16 v[10:13], v[162:165], v[202:205], v[10:13]
	v_mfma_f32_16x16x32_bf16 v[62:65], v[136:139], v[210:213], v[62:65]
	v_mfma_f32_16x16x32_bf16 v[6:9], v[162:165], v[210:213], v[6:9]
	v_mfma_f32_16x16x32_bf16 v[82:85], v[158:161], v[174:177], v[82:85]
	v_mfma_f32_16x16x32_bf16 v[26:29], v[166:169], v[174:177], v[26:29]
	v_mfma_f32_16x16x32_bf16 v[74:77], v[158:161], v[198:201], v[74:77]
	v_mfma_f32_16x16x32_bf16 v[18:21], v[166:169], v[198:201], v[18:21]
	v_mfma_f32_16x16x32_bf16 v[66:69], v[158:161], v[206:209], v[66:69]
	v_mfma_f32_16x16x32_bf16 v[10:13], v[166:169], v[206:209], v[10:13]
	v_mfma_f32_16x16x32_bf16 v[62:65], v[158:161], v[214:217], v[62:65]
	v_mfma_f32_16x16x32_bf16 v[6:9], v[166:169], v[214:217], v[6:9]
	s_setprio 0
	s_barrier
	s_add_i32 s76, 0, 0x18000
	s_add_i32 s77, 0, 0x1c000
	s_add_u32 s28, s28, 0x40000
	s_addc_u32 s29, s29, 0
	s_mov_b32 m0, s67
	s_nop 0
	global_load_lds_dwordx4 v188, s[28:29]
	s_mov_b32 m0, s44
	s_nop 0
	global_load_lds_dwordx4 v190, s[28:29]
	v_add_u32_e32 v118, s76, v220
	ds_read_b128 v[106:109], v118
	ds_read_b128 v[110:113], v118 offset:1024
	ds_read_b128 v[128:131], v118 offset:2048
	ds_read_b128 v[132:135], v118 offset:3072
	v_add_u32_e32 v118, s77, v220
	ds_read_b128 v[136:139], v118
	ds_read_b128 v[158:161], v118 offset:1024
	ds_read_b128 v[162:165], v118 offset:2048
	ds_read_b128 v[166:169], v118 offset:3072
	ds_read_b128 v[170:173], v234 offset:32768
	ds_read_b128 v[174:177], v234 offset:33792
	ds_read_b128 v[178:181], v234 offset:34816
	ds_read_b128 v[198:201], v234 offset:35840
	ds_read_b128 v[202:205], v234 offset:36864
	ds_read_b128 v[206:209], v234 offset:37888
	ds_read_b128 v[210:213], v234 offset:38912
	ds_read_b128 v[214:217], v234 offset:39936
	s_waitcnt vmcnt(8)
	s_waitcnt lgkmcnt(0)
	s_barrier
	s_setprio 1
	v_mfma_f32_16x16x32_bf16 v[124:127], v[106:109], v[170:173], v[124:127]
	v_mfma_f32_16x16x32_bf16 v[98:101], v[128:131], v[170:173], v[98:101]
	v_mfma_f32_16x16x32_bf16 v[154:157], v[106:109], v[178:181], v[154:157]
	v_mfma_f32_16x16x32_bf16 v[58:61], v[128:131], v[178:181], v[58:61]
	v_mfma_f32_16x16x32_bf16 v[144:147], v[106:109], v[202:205], v[146:149]
	v_mfma_f32_16x16x32_bf16 v[46:49], v[128:131], v[202:205], v[46:49]
	v_mfma_f32_16x16x32_bf16 v[102:105], v[106:109], v[210:213], v[102:105]
	v_mfma_f32_16x16x32_bf16 v[54:57], v[128:131], v[210:213], v[54:57]
	v_mfma_f32_16x16x32_bf16 v[124:127], v[110:113], v[174:177], v[124:127]
	v_mfma_f32_16x16x32_bf16 v[98:101], v[132:135], v[174:177], v[98:101]
	v_mfma_f32_16x16x32_bf16 v[154:157], v[110:113], v[198:201], v[154:157]
	v_mfma_f32_16x16x32_bf16 v[58:61], v[132:135], v[198:201], v[58:61]
	v_mfma_f32_16x16x32_bf16 v[146:149], v[110:113], v[206:209], v[144:147]
	v_mfma_f32_16x16x32_bf16 v[46:49], v[132:135], v[206:209], v[46:49]
	v_mfma_f32_16x16x32_bf16 v[102:105], v[110:113], v[214:217], v[102:105]
	v_mfma_f32_16x16x32_bf16 v[54:57], v[132:135], v[214:217], v[54:57]
	v_mfma_f32_16x16x32_bf16 v[118:121], v[136:139], v[170:173], v[120:123]
	v_mfma_f32_16x16x32_bf16 v[94:97], v[162:165], v[170:173], v[94:97]
	v_mfma_f32_16x16x32_bf16 v[150:153], v[136:139], v[178:181], v[150:153]
	v_mfma_f32_16x16x32_bf16 v[50:53], v[162:165], v[178:181], v[50:53]
	v_mfma_f32_16x16x32_bf16 v[140:143], v[136:139], v[202:205], v[140:143]
	v_mfma_f32_16x16x32_bf16 v[42:45], v[162:165], v[202:205], v[42:45]
	v_mfma_f32_16x16x32_bf16 v[114:117], v[136:139], v[210:213], v[114:117]
	v_mfma_f32_16x16x32_bf16 v[38:41], v[162:165], v[210:213], v[38:41]
	v_mfma_f32_16x16x32_bf16 v[120:123], v[158:161], v[174:177], v[118:121]
	v_mfma_f32_16x16x32_bf16 v[94:97], v[166:169], v[174:177], v[94:97]
	v_mfma_f32_16x16x32_bf16 v[150:153], v[158:161], v[198:201], v[150:153]
	v_mfma_f32_16x16x32_bf16 v[50:53], v[166:169], v[198:201], v[50:53]
	v_mfma_f32_16x16x32_bf16 v[142:145], v[158:161], v[206:209], v[140:143]
	v_mfma_f32_16x16x32_bf16 v[42:45], v[166:169], v[206:209], v[42:45]
	v_mfma_f32_16x16x32_bf16 v[116:119], v[158:161], v[214:217], v[114:117]
	v_mfma_f32_16x16x32_bf16 v[38:41], v[166:169], v[214:217], v[38:41]
	s_setprio 0
	s_barrier
	s_add_i32 s100, s76, s42
	s_mov_b32 m0, s100
	s_add_u32 s24, s24, 0x80
	s_addc_u32 s25, s25, 0
	global_load_lds_dwordx4 v0, s[24:25]
	s_add_i32 m0, s100, 0x2000
	s_add_i32 s100, s77, s42
	global_load_lds_dwordx4 v192, s[24:25]
	s_add_u32 s24, s24, 0x40000
	s_addc_u32 s25, s25, 0
	s_mov_b32 m0, s100
	s_add_i32 s100, s100, 0x2000
	global_load_lds_dwordx4 v0, s[24:25]
	s_mov_b32 m0, s100
	s_add_u32 s28, s28, 0xfffc0080
	s_addc_u32 s29, s29, -1
	global_load_lds_dwordx4 v192, s[24:25]
	s_mov_b32 m0, s45
	s_nop 0
	global_load_lds_dwordx4 v188, s[28:29]
	s_mov_b32 m0, s70
	s_nop 0
	global_load_lds_dwordx4 v190, s[28:29]
	ds_read_b128 v[170:173], v234 offset:49152
	ds_read_b128 v[174:177], v234 offset:50176
	ds_read_b128 v[178:181], v234 offset:51200
	ds_read_b128 v[198:201], v234 offset:52224
	ds_read_b128 v[202:205], v234 offset:53248
	ds_read_b128 v[206:209], v234 offset:54272
	ds_read_b128 v[210:213], v234 offset:55296
	ds_read_b128 v[214:217], v234 offset:56320
	s_waitcnt vmcnt(8)
	s_waitcnt lgkmcnt(0)
	s_barrier
	s_setprio 1
	v_mfma_f32_16x16x32_bf16 v[86:89], v[106:109], v[170:173], v[86:89]
	v_mfma_f32_16x16x32_bf16 v[30:33], v[128:131], v[170:173], v[30:33]
	v_mfma_f32_16x16x32_bf16 v[78:81], v[106:109], v[178:181], v[78:81]
	v_mfma_f32_16x16x32_bf16 v[22:25], v[128:131], v[178:181], v[22:25]
	v_mfma_f32_16x16x32_bf16 v[70:73], v[106:109], v[202:205], v[70:73]
	v_mfma_f32_16x16x32_bf16 v[14:17], v[128:131], v[202:205], v[14:17]
	v_mfma_f32_16x16x32_bf16 v[90:93], v[106:109], v[210:213], v[90:93]
	v_mfma_f32_16x16x32_bf16 v[34:37], v[128:131], v[210:213], v[34:37]
	v_mfma_f32_16x16x32_bf16 v[86:89], v[110:113], v[174:177], v[86:89]
	v_mfma_f32_16x16x32_bf16 v[30:33], v[132:135], v[174:177], v[30:33]
	v_mfma_f32_16x16x32_bf16 v[78:81], v[110:113], v[198:201], v[78:81]
	v_mfma_f32_16x16x32_bf16 v[22:25], v[132:135], v[198:201], v[22:25]
	v_mfma_f32_16x16x32_bf16 v[70:73], v[110:113], v[206:209], v[70:73]
	v_mfma_f32_16x16x32_bf16 v[14:17], v[132:135], v[206:209], v[14:17]
	v_mfma_f32_16x16x32_bf16 v[90:93], v[110:113], v[214:217], v[90:93]
	v_mfma_f32_16x16x32_bf16 v[34:37], v[132:135], v[214:217], v[34:37]
	v_mfma_f32_16x16x32_bf16 v[82:85], v[136:139], v[170:173], v[82:85]
	v_mfma_f32_16x16x32_bf16 v[26:29], v[162:165], v[170:173], v[26:29]
	v_mfma_f32_16x16x32_bf16 v[74:77], v[136:139], v[178:181], v[74:77]
	v_mfma_f32_16x16x32_bf16 v[18:21], v[162:165], v[178:181], v[18:21]
	v_mfma_f32_16x16x32_bf16 v[66:69], v[136:139], v[202:205], v[66:69]
	v_mfma_f32_16x16x32_bf16 v[10:13], v[162:165], v[202:205], v[10:13]
	v_mfma_f32_16x16x32_bf16 v[62:65], v[136:139], v[210:213], v[62:65]
	v_mfma_f32_16x16x32_bf16 v[6:9], v[162:165], v[210:213], v[6:9]
	v_mfma_f32_16x16x32_bf16 v[82:85], v[158:161], v[174:177], v[82:85]
	v_mfma_f32_16x16x32_bf16 v[26:29], v[166:169], v[174:177], v[26:29]
	v_mfma_f32_16x16x32_bf16 v[74:77], v[158:161], v[198:201], v[74:77]
	v_mfma_f32_16x16x32_bf16 v[18:21], v[166:169], v[198:201], v[18:21]
	v_mfma_f32_16x16x32_bf16 v[66:69], v[158:161], v[206:209], v[66:69]
	v_mfma_f32_16x16x32_bf16 v[10:13], v[166:169], v[206:209], v[10:13]
	v_mfma_f32_16x16x32_bf16 v[62:65], v[158:161], v[214:217], v[62:65]
	v_mfma_f32_16x16x32_bf16 v[6:9], v[166:169], v[214:217], v[6:9]
	s_setprio 0
	s_barrier
	s_add_i32 vcc_lo, vcc_lo, 2
	s_add_u32 s22, s22, 0x100
	s_addc_u32 s23, s23, 0
	s_add_u32 s81, s81, 0x100
	s_addc_u32 s99, s99, 0
	s_cmp_gt_u32 vcc_lo, 13
	s_cbranch_scc0 .LBB0_453
	s_and_b64 vcc, exec, s[26:27]
	s_cbranch_vccz .LBB0_456
	s_barrier

.LBB0_711:
	s_add_u32 s8, s10, 0xfffc0080
	s_addc_u32 s9, s11, -1
	s_add_i32 s67, 0, 0x10000
	s_cmp_eq_u32 s51, 12
	s_cselect_b32 s13, s25, s9
	s_cselect_b32 s12, s27, s8
	s_cselect_b32 s9, s29, s50
	s_cselect_b32 s8, s44, s45
	s_add_i32 s72, 0, 0x14000
	s_add_i32 m0, s68, 0xc000
	s_nop 0
	global_load_lds_dwordx4 v192, s[10:11]
	s_add_i32 m0, s68, 0xe000
	s_nop 0
	global_load_lds_dwordx4 v194, s[10:11]
	v_add_u32_e32 v146, s67, v245
	v_add_u32_e32 v162, s72, v245
	ds_read_b128 v[134:137], v146
	ds_read_b128 v[138:141], v146 offset:1024
	ds_read_b128 v[142:145], v146 offset:2048
	ds_read_b128 v[146:149], v146 offset:3072
	ds_read_b128 v[150:153], v162
	ds_read_b128 v[154:157], v162 offset:1024
	ds_read_b128 v[158:161], v162 offset:2048
	ds_read_b128 v[162:165], v162 offset:3072
	ds_read_b128 v[166:169], v247
	ds_read_b128 v[170:173], v247 offset:1024
	ds_read_b128 v[174:177], v247 offset:2048
	ds_read_b128 v[178:181], v247 offset:3072
	ds_read_b128 v[196:199], v247 offset:4096
	ds_read_b128 v[200:203], v247 offset:5120
	ds_read_b128 v[204:207], v247 offset:6144
	ds_read_b128 v[208:211], v247 offset:7168
	s_waitcnt vmcnt(8)
	s_waitcnt lgkmcnt(0)
	s_barrier
	s_setprio 1
	v_mfma_f32_16x16x32_bf16 v[130:133], v[134:137], v[166:169], v[130:133]
	v_mfma_f32_16x16x32_bf16 v[126:129], v[142:145], v[166:169], v[126:129]
	v_mfma_f32_16x16x32_bf16 v[114:117], v[134:137], v[174:177], v[114:117]
	v_mfma_f32_16x16x32_bf16 v[110:113], v[142:145], v[174:177], v[110:113]
	v_mfma_f32_16x16x32_bf16 v[98:101], v[134:137], v[196:199], v[98:101]
	v_mfma_f32_16x16x32_bf16 v[94:97], v[142:145], v[196:199], v[94:97]
	v_mfma_f32_16x16x32_bf16 v[82:85], v[134:137], v[204:207], v[82:85]
	v_mfma_f32_16x16x32_bf16 v[78:81], v[142:145], v[204:207], v[78:81]
	v_mfma_f32_16x16x32_bf16 v[130:133], v[138:141], v[170:173], v[130:133]
	v_mfma_f32_16x16x32_bf16 v[126:129], v[146:149], v[170:173], v[126:129]
	v_mfma_f32_16x16x32_bf16 v[114:117], v[138:141], v[178:181], v[114:117]
	v_mfma_f32_16x16x32_bf16 v[110:113], v[146:149], v[178:181], v[110:113]
	v_mfma_f32_16x16x32_bf16 v[98:101], v[138:141], v[200:203], v[98:101]
	v_mfma_f32_16x16x32_bf16 v[94:97], v[146:149], v[200:203], v[94:97]
	v_mfma_f32_16x16x32_bf16 v[82:85], v[138:141], v[208:211], v[82:85]
	v_mfma_f32_16x16x32_bf16 v[78:81], v[146:149], v[208:211], v[78:81]
	v_mfma_f32_16x16x32_bf16 v[122:125], v[150:153], v[166:169], v[122:125]
	v_mfma_f32_16x16x32_bf16 v[118:121], v[158:161], v[166:169], v[118:121]
	v_mfma_f32_16x16x32_bf16 v[106:109], v[150:153], v[174:177], v[106:109]
	v_mfma_f32_16x16x32_bf16 v[102:105], v[158:161], v[174:177], v[102:105]
	v_mfma_f32_16x16x32_bf16 v[90:93], v[150:153], v[196:199], v[90:93]
	v_mfma_f32_16x16x32_bf16 v[86:89], v[158:161], v[196:199], v[86:89]
	v_mfma_f32_16x16x32_bf16 v[74:77], v[150:153], v[204:207], v[74:77]
	v_mfma_f32_16x16x32_bf16 v[70:73], v[158:161], v[204:207], v[70:73]
	v_mfma_f32_16x16x32_bf16 v[122:125], v[154:157], v[170:173], v[122:125]
	v_mfma_f32_16x16x32_bf16 v[118:121], v[162:165], v[170:173], v[118:121]
	v_mfma_f32_16x16x32_bf16 v[106:109], v[154:157], v[178:181], v[106:109]
	v_mfma_f32_16x16x32_bf16 v[102:105], v[162:165], v[178:181], v[102:105]
	v_mfma_f32_16x16x32_bf16 v[90:93], v[154:157], v[200:203], v[90:93]
	v_mfma_f32_16x16x32_bf16 v[86:89], v[162:165], v[200:203], v[86:89]
	v_mfma_f32_16x16x32_bf16 v[74:77], v[154:157], v[208:211], v[74:77]
	v_mfma_f32_16x16x32_bf16 v[70:73], v[162:165], v[208:211], v[70:73]
	s_setprio 0
	s_barrier
	s_add_i32 s67, s67, s63
	s_mov_b32 m0, s67
	s_nop 0
	global_load_lds_dwordx4 v0, s[8:9]
	s_add_i32 m0, s67, 0x2000
	s_add_u32 s70, s8, 0x40000
	s_addc_u32 s71, s9, 0
	s_add_i32 s67, s72, s63
	global_load_lds_dwordx4 v190, s[8:9]
	s_mov_b32 m0, s67
	s_nop 0
	global_load_lds_dwordx4 v0, s[70:71]
	s_add_i32 m0, s67, 0x2000
	s_nop 0
	global_load_lds_dwordx4 v190, s[70:71]
	s_mov_b32 m0, s68
	s_nop 0
	global_load_lds_dwordx4 v182, s[12:13]
	s_mov_b32 m0, s69
	s_nop 0
	global_load_lds_dwordx4 v188, s[12:13]
	ds_read_b128 v[166:169], v247 offset:16384
	ds_read_b128 v[170:173], v247 offset:17408
	ds_read_b128 v[174:177], v247 offset:18432
	ds_read_b128 v[178:181], v247 offset:19456
	ds_read_b128 v[196:199], v247 offset:20480
	ds_read_b128 v[200:203], v247 offset:21504
	ds_read_b128 v[204:207], v247 offset:22528
	ds_read_b128 v[208:211], v247 offset:23552
	s_waitcnt vmcnt(8)
	s_waitcnt lgkmcnt(0)
	s_barrier
	s_setprio 1
	v_mfma_f32_16x16x32_bf16 v[66:69], v[134:137], v[166:169], v[66:69]
	v_mfma_f32_16x16x32_bf16 v[62:65], v[142:145], v[166:169], v[62:65]
	v_mfma_f32_16x16x32_bf16 v[50:53], v[134:137], v[174:177], v[50:53]
	v_mfma_f32_16x16x32_bf16 v[46:49], v[142:145], v[174:177], v[46:49]
	v_mfma_f32_16x16x32_bf16 v[34:37], v[134:137], v[196:199], v[34:37]
	v_mfma_f32_16x16x32_bf16 v[30:33], v[142:145], v[196:199], v[30:33]
	v_mfma_f32_16x16x32_bf16 v[18:21], v[134:137], v[204:207], v[18:21]
	v_mfma_f32_16x16x32_bf16 v[14:17], v[142:145], v[204:207], v[14:17]
	v_mfma_f32_16x16x32_bf16 v[66:69], v[138:141], v[170:173], v[66:69]
	v_mfma_f32_16x16x32_bf16 v[62:65], v[146:149], v[170:173], v[62:65]
	v_mfma_f32_16x16x32_bf16 v[50:53], v[138:141], v[178:181], v[50:53]
	v_mfma_f32_16x16x32_bf16 v[46:49], v[146:149], v[178:181], v[46:49]
	v_mfma_f32_16x16x32_bf16 v[34:37], v[138:141], v[200:203], v[34:37]
	v_mfma_f32_16x16x32_bf16 v[30:33], v[146:149], v[200:203], v[30:33]
	v_mfma_f32_16x16x32_bf16 v[18:21], v[138:141], v[208:211], v[18:21]
	v_mfma_f32_16x16x32_bf16 v[14:17], v[146:149], v[208:211], v[14:17]
	v_mfma_f32_16x16x32_bf16 v[58:61], v[150:153], v[166:169], v[58:61]
	v_mfma_f32_16x16x32_bf16 v[54:57], v[158:161], v[166:169], v[54:57]
	v_mfma_f32_16x16x32_bf16 v[42:45], v[150:153], v[174:177], v[42:45]
	v_mfma_f32_16x16x32_bf16 v[38:41], v[158:161], v[174:177], v[38:41]
	v_mfma_f32_16x16x32_bf16 v[26:29], v[150:153], v[196:199], v[26:29]
	v_mfma_f32_16x16x32_bf16 v[22:25], v[158:161], v[196:199], v[22:25]
	v_mfma_f32_16x16x32_bf16 v[10:13], v[150:153], v[204:207], v[10:13]
	v_mfma_f32_16x16x32_bf16 v[6:9], v[158:161], v[204:207], v[6:9]
	v_mfma_f32_16x16x32_bf16 v[58:61], v[154:157], v[170:173], v[58:61]
	v_mfma_f32_16x16x32_bf16 v[54:57], v[162:165], v[170:173], v[54:57]
	v_mfma_f32_16x16x32_bf16 v[42:45], v[154:157], v[178:181], v[42:45]
	v_mfma_f32_16x16x32_bf16 v[38:41], v[162:165], v[178:181], v[38:41]
	v_mfma_f32_16x16x32_bf16 v[26:29], v[154:157], v[200:203], v[26:29]
	v_mfma_f32_16x16x32_bf16 v[22:25], v[162:165], v[200:203], v[22:25]
	v_mfma_f32_16x16x32_bf16 v[10:13], v[154:157], v[208:211], v[10:13]
	v_mfma_f32_16x16x32_bf16 v[6:9], v[162:165], v[208:211], v[6:9]
	s_setprio 0
	s_barrier
	s_add_i32 s67, 0, 0x18000
	s_add_i32 s70, 0, 0x1c000
	s_add_u32 s12, s12, 0x40000
	s_addc_u32 s13, s13, 0
	s_mov_b32 m0, s78
	s_nop 0
	global_load_lds_dwordx4 v182, s[12:13]
	s_mov_b32 m0, s79
	s_nop 0
	global_load_lds_dwordx4 v188, s[12:13]
	v_add_u32_e32 v146, s67, v245
	v_add_u32_e32 v162, s70, v245
	ds_read_b128 v[134:137], v146
	ds_read_b128 v[138:141], v146 offset:1024
	ds_read_b128 v[142:145], v146 offset:2048
	ds_read_b128 v[146:149], v146 offset:3072
	ds_read_b128 v[150:153], v162
	ds_read_b128 v[154:157], v162 offset:1024
	ds_read_b128 v[158:161], v162 offset:2048
	ds_read_b128 v[162:165], v162 offset:3072
	ds_read_b128 v[166:169], v247 offset:32768
	ds_read_b128 v[170:173], v247 offset:33792
	ds_read_b128 v[174:177], v247 offset:34816
	ds_read_b128 v[178:181], v247 offset:35840
	ds_read_b128 v[196:199], v247 offset:36864
	ds_read_b128 v[200:203], v247 offset:37888
	ds_read_b128 v[204:207], v247 offset:38912
	ds_read_b128 v[208:211], v247 offset:39936
	s_waitcnt vmcnt(8)
	s_waitcnt lgkmcnt(0)
	s_barrier
	s_setprio 1
	v_mfma_f32_16x16x32_bf16 v[130:133], v[134:137], v[166:169], v[130:133]
	v_mfma_f32_16x16x32_bf16 v[126:129], v[142:145], v[166:169], v[126:129]
	v_mfma_f32_16x16x32_bf16 v[114:117], v[134:137], v[174:177], v[114:117]
	v_mfma_f32_16x16x32_bf16 v[110:113], v[142:145], v[174:177], v[110:113]
	v_mfma_f32_16x16x32_bf16 v[98:101], v[134:137], v[196:199], v[98:101]
	v_mfma_f32_16x16x32_bf16 v[94:97], v[142:145], v[196:199], v[94:97]
	v_mfma_f32_16x16x32_bf16 v[82:85], v[134:137], v[204:207], v[82:85]
	v_mfma_f32_16x16x32_bf16 v[78:81], v[142:145], v[204:207], v[78:81]
	v_mfma_f32_16x16x32_bf16 v[130:133], v[138:141], v[170:173], v[130:133]
	v_mfma_f32_16x16x32_bf16 v[126:129], v[146:149], v[170:173], v[126:129]
	v_mfma_f32_16x16x32_bf16 v[114:117], v[138:141], v[178:181], v[114:117]
	v_mfma_f32_16x16x32_bf16 v[110:113], v[146:149], v[178:181], v[110:113]
	v_mfma_f32_16x16x32_bf16 v[98:101], v[138:141], v[200:203], v[98:101]
	v_mfma_f32_16x16x32_bf16 v[94:97], v[146:149], v[200:203], v[94:97]
	v_mfma_f32_16x16x32_bf16 v[82:85], v[138:141], v[208:211], v[82:85]
	v_mfma_f32_16x16x32_bf16 v[78:81], v[146:149], v[208:211], v[78:81]
	v_mfma_f32_16x16x32_bf16 v[122:125], v[150:153], v[166:169], v[122:125]
	v_mfma_f32_16x16x32_bf16 v[118:121], v[158:161], v[166:169], v[118:121]
	v_mfma_f32_16x16x32_bf16 v[106:109], v[150:153], v[174:177], v[106:109]
	v_mfma_f32_16x16x32_bf16 v[102:105], v[158:161], v[174:177], v[102:105]
	v_mfma_f32_16x16x32_bf16 v[90:93], v[150:153], v[196:199], v[90:93]
	v_mfma_f32_16x16x32_bf16 v[86:89], v[158:161], v[196:199], v[86:89]
	v_mfma_f32_16x16x32_bf16 v[74:77], v[150:153], v[204:207], v[74:77]
	v_mfma_f32_16x16x32_bf16 v[70:73], v[158:161], v[204:207], v[70:73]
	v_mfma_f32_16x16x32_bf16 v[122:125], v[154:157], v[170:173], v[122:125]
	v_mfma_f32_16x16x32_bf16 v[118:121], v[162:165], v[170:173], v[118:121]
	v_mfma_f32_16x16x32_bf16 v[106:109], v[154:157], v[178:181], v[106:109]
	v_mfma_f32_16x16x32_bf16 v[102:105], v[162:165], v[178:181], v[102:105]
	v_mfma_f32_16x16x32_bf16 v[90:93], v[154:157], v[200:203], v[90:93]
	v_mfma_f32_16x16x32_bf16 v[86:89], v[162:165], v[200:203], v[86:89]
	v_mfma_f32_16x16x32_bf16 v[74:77], v[154:157], v[208:211], v[74:77]
	v_mfma_f32_16x16x32_bf16 v[70:73], v[162:165], v[208:211], v[70:73]
	s_setprio 0
	s_barrier
	s_add_i32 s100, s67, s63
	s_mov_b32 m0, s100
	s_add_u32 s8, s8, 0x80
	s_addc_u32 s9, s9, 0
	global_load_lds_dwordx4 v0, s[8:9]
	s_add_i32 m0, s100, 0x2000
	s_add_i32 s100, s70, s63
	global_load_lds_dwordx4 v190, s[8:9]
	s_add_u32 s8, s8, 0x40000
	s_addc_u32 s9, s9, 0
	s_mov_b32 m0, s100
	s_add_i32 s100, s100, 0x2000
	global_load_lds_dwordx4 v0, s[8:9]
	s_mov_b32 m0, s100
	s_add_u32 s12, s12, 0xfffc0080
	s_addc_u32 s13, s13, -1
	global_load_lds_dwordx4 v190, s[8:9]
	s_mov_b32 m0, s80
	s_nop 0
	global_load_lds_dwordx4 v182, s[12:13]
	s_mov_b32 m0, s81
	s_nop 0
	global_load_lds_dwordx4 v188, s[12:13]
	ds_read_b128 v[166:169], v247 offset:49152
	ds_read_b128 v[170:173], v247 offset:50176
	ds_read_b128 v[174:177], v247 offset:51200
	ds_read_b128 v[178:181], v247 offset:52224
	ds_read_b128 v[196:199], v247 offset:53248
	ds_read_b128 v[200:203], v247 offset:54272
	ds_read_b128 v[204:207], v247 offset:55296
	ds_read_b128 v[208:211], v247 offset:56320
	s_waitcnt vmcnt(8)
	s_waitcnt lgkmcnt(0)
	s_barrier
	s_setprio 1
	v_mfma_f32_16x16x32_bf16 v[66:69], v[134:137], v[166:169], v[66:69]
	v_mfma_f32_16x16x32_bf16 v[62:65], v[142:145], v[166:169], v[62:65]
	v_mfma_f32_16x16x32_bf16 v[50:53], v[134:137], v[174:177], v[50:53]
	v_mfma_f32_16x16x32_bf16 v[46:49], v[142:145], v[174:177], v[46:49]
	v_mfma_f32_16x16x32_bf16 v[34:37], v[134:137], v[196:199], v[34:37]
	v_mfma_f32_16x16x32_bf16 v[30:33], v[142:145], v[196:199], v[30:33]
	v_mfma_f32_16x16x32_bf16 v[18:21], v[134:137], v[204:207], v[18:21]
	v_mfma_f32_16x16x32_bf16 v[14:17], v[142:145], v[204:207], v[14:17]
	v_mfma_f32_16x16x32_bf16 v[66:69], v[138:141], v[170:173], v[66:69]
	v_mfma_f32_16x16x32_bf16 v[62:65], v[146:149], v[170:173], v[62:65]
	v_mfma_f32_16x16x32_bf16 v[50:53], v[138:141], v[178:181], v[50:53]
	v_mfma_f32_16x16x32_bf16 v[46:49], v[146:149], v[178:181], v[46:49]
	v_mfma_f32_16x16x32_bf16 v[34:37], v[138:141], v[200:203], v[34:37]
	v_mfma_f32_16x16x32_bf16 v[30:33], v[146:149], v[200:203], v[30:33]
	v_mfma_f32_16x16x32_bf16 v[18:21], v[138:141], v[208:211], v[18:21]
	v_mfma_f32_16x16x32_bf16 v[14:17], v[146:149], v[208:211], v[14:17]
	v_mfma_f32_16x16x32_bf16 v[58:61], v[150:153], v[166:169], v[58:61]
	v_mfma_f32_16x16x32_bf16 v[54:57], v[158:161], v[166:169], v[54:57]
	v_mfma_f32_16x16x32_bf16 v[42:45], v[150:153], v[174:177], v[42:45]
	v_mfma_f32_16x16x32_bf16 v[38:41], v[158:161], v[174:177], v[38:41]
	v_mfma_f32_16x16x32_bf16 v[26:29], v[150:153], v[196:199], v[26:29]
	v_mfma_f32_16x16x32_bf16 v[22:25], v[158:161], v[196:199], v[22:25]
	v_mfma_f32_16x16x32_bf16 v[10:13], v[150:153], v[204:207], v[10:13]
	v_mfma_f32_16x16x32_bf16 v[6:9], v[158:161], v[204:207], v[6:9]
	v_mfma_f32_16x16x32_bf16 v[58:61], v[154:157], v[170:173], v[58:61]
	v_mfma_f32_16x16x32_bf16 v[54:57], v[162:165], v[170:173], v[54:57]
	v_mfma_f32_16x16x32_bf16 v[42:45], v[154:157], v[178:181], v[42:45]
	v_mfma_f32_16x16x32_bf16 v[38:41], v[162:165], v[178:181], v[38:41]
	v_mfma_f32_16x16x32_bf16 v[26:29], v[154:157], v[200:203], v[26:29]
	v_mfma_f32_16x16x32_bf16 v[22:25], v[162:165], v[200:203], v[22:25]
	v_mfma_f32_16x16x32_bf16 v[10:13], v[154:157], v[208:211], v[10:13]
	v_mfma_f32_16x16x32_bf16 v[6:9], v[162:165], v[208:211], v[6:9]
	s_setprio 0
	s_barrier
	s_add_i32 s51, s51, 2
	s_add_u32 s10, s10, 0x100
	s_addc_u32 s11, s11, 0
	s_add_u32 s45, s45, 0x100
	s_addc_u32 s50, s50, 0
	s_cmp_gt_u32 s51, 13
	s_cbranch_scc0 .LBB0_711
	s_and_b64 vcc, exec, s[20:21]
	s_cbranch_vccz .LBB0_714
	s_barrier

.LBB0_1065:
	s_add_i32 s44, s26, 2
	s_add_u32 s45, s10, 0x80
	s_addc_u32 s27, s11, 0
	s_add_i32 s72, 0, 0x10000
	s_cmp_eq_u32 s68, s26
	s_cselect_b32 s27, s25, s27
	s_cselect_b32 s26, s24, s45
	s_cselect_b32 s71, s29, s31
	s_cselect_b32 s70, s28, s30
	s_add_i32 s45, 0, 0x14000
	s_add_i32 m0, s57, 0xc000
	s_nop 0
	global_load_lds_dwordx4 v192, s[10:11]
	s_add_i32 m0, s57, 0xe000
	s_nop 0
	global_load_lds_dwordx4 v194, s[10:11]
	v_add_u32_e32 v114, s72, v217
	v_add_u32_e32 v162, s45, v217
	ds_read_b128 v[94:97], v114
	ds_read_b128 v[102:105], v114 offset:1024
	ds_read_b128 v[110:113], v114 offset:2048
	ds_read_b128 v[114:117], v114 offset:3072
	ds_read_b128 v[150:153], v162
	ds_read_b128 v[154:157], v162 offset:1024
	ds_read_b128 v[158:161], v162 offset:2048
	ds_read_b128 v[162:165], v162 offset:3072
	ds_read_b128 v[166:169], v236
	ds_read_b128 v[170:173], v236 offset:1024
	ds_read_b128 v[174:177], v236 offset:2048
	ds_read_b128 v[178:181], v236 offset:3072
	ds_read_b128 v[196:199], v236 offset:4096
	ds_read_b128 v[200:203], v236 offset:5120
	ds_read_b128 v[204:207], v236 offset:6144
	ds_read_b128 v[208:211], v236 offset:7168
	s_waitcnt vmcnt(8)
	s_waitcnt lgkmcnt(0)
	s_barrier
	s_setprio 1
	v_mfma_f32_16x16x32_bf16 v[146:149], v[94:97], v[166:169], v[146:149]
	v_mfma_f32_16x16x32_bf16 v[142:145], v[110:113], v[166:169], v[142:145]
	v_mfma_f32_16x16x32_bf16 v[130:133], v[94:97], v[174:177], v[130:133]
	v_mfma_f32_16x16x32_bf16 v[126:129], v[110:113], v[174:177], v[126:129]
	v_mfma_f32_16x16x32_bf16 v[106:109], v[94:97], v[196:199], v[106:109]
	v_mfma_f32_16x16x32_bf16 v[98:101], v[110:113], v[196:199], v[98:101]
	v_mfma_f32_16x16x32_bf16 v[82:85], v[94:97], v[204:207], v[82:85]
	v_mfma_f32_16x16x32_bf16 v[78:81], v[110:113], v[204:207], v[78:81]
	v_mfma_f32_16x16x32_bf16 v[146:149], v[102:105], v[170:173], v[146:149]
	v_mfma_f32_16x16x32_bf16 v[142:145], v[114:117], v[170:173], v[142:145]
	v_mfma_f32_16x16x32_bf16 v[130:133], v[102:105], v[178:181], v[130:133]
	v_mfma_f32_16x16x32_bf16 v[126:129], v[114:117], v[178:181], v[126:129]
	v_mfma_f32_16x16x32_bf16 v[106:109], v[102:105], v[200:203], v[106:109]
	v_mfma_f32_16x16x32_bf16 v[98:101], v[114:117], v[200:203], v[98:101]
	v_mfma_f32_16x16x32_bf16 v[82:85], v[102:105], v[208:211], v[82:85]
	v_mfma_f32_16x16x32_bf16 v[78:81], v[114:117], v[208:211], v[78:81]
	v_mfma_f32_16x16x32_bf16 v[138:141], v[150:153], v[166:169], v[138:141]
	v_mfma_f32_16x16x32_bf16 v[134:137], v[158:161], v[166:169], v[134:137]
	v_mfma_f32_16x16x32_bf16 v[122:125], v[150:153], v[174:177], v[122:125]
	v_mfma_f32_16x16x32_bf16 v[118:121], v[158:161], v[174:177], v[118:121]
	v_mfma_f32_16x16x32_bf16 v[90:93], v[150:153], v[196:199], v[90:93]
	v_mfma_f32_16x16x32_bf16 v[86:89], v[158:161], v[196:199], v[86:89]
	v_mfma_f32_16x16x32_bf16 v[74:77], v[150:153], v[204:207], v[74:77]
	v_mfma_f32_16x16x32_bf16 v[70:73], v[158:161], v[204:207], v[70:73]
	v_mfma_f32_16x16x32_bf16 v[138:141], v[154:157], v[170:173], v[138:141]
	v_mfma_f32_16x16x32_bf16 v[134:137], v[162:165], v[170:173], v[134:137]
	v_mfma_f32_16x16x32_bf16 v[122:125], v[154:157], v[178:181], v[122:125]
	v_mfma_f32_16x16x32_bf16 v[118:121], v[162:165], v[178:181], v[118:121]
	v_mfma_f32_16x16x32_bf16 v[90:93], v[154:157], v[200:203], v[90:93]
	v_mfma_f32_16x16x32_bf16 v[86:89], v[162:165], v[200:203], v[86:89]
	v_mfma_f32_16x16x32_bf16 v[74:77], v[154:157], v[208:211], v[74:77]
	v_mfma_f32_16x16x32_bf16 v[70:73], v[162:165], v[208:211], v[70:73]
	s_setprio 0
	s_barrier
	s_add_i32 s72, s72, s54
	s_mov_b32 m0, s72
	s_nop 0
	global_load_lds_dwordx4 v0, s[70:71]
	s_add_i32 m0, s72, 0x2000
	s_add_u32 s100, s70, 0x80
	s_addc_u32 s101, s71, 0
	global_load_lds_dwordx4 v190, s[70:71]
	s_add_u32 s70, s70, s42
	s_addc_u32 s71, s71, 0
	s_add_i32 s45, s45, s54
	s_mov_b32 m0, s45
	s_nop 0
	global_load_lds_dwordx4 v0, s[70:71]
	s_add_i32 m0, s45, 0x2000
	s_nop 0
	global_load_lds_dwordx4 v190, s[70:71]
	s_mov_b32 m0, s57
	s_nop 0
	global_load_lds_dwordx4 v182, s[26:27]
	s_mov_b32 m0, s58
	s_nop 0
	global_load_lds_dwordx4 v188, s[26:27]
	ds_read_b128 v[166:169], v236 offset:16384
	ds_read_b128 v[170:173], v236 offset:17408
	ds_read_b128 v[174:177], v236 offset:18432
	ds_read_b128 v[178:181], v236 offset:19456
	ds_read_b128 v[196:199], v236 offset:20480
	ds_read_b128 v[200:203], v236 offset:21504
	ds_read_b128 v[204:207], v236 offset:22528
	ds_read_b128 v[208:211], v236 offset:23552
	s_waitcnt vmcnt(8)
	s_waitcnt lgkmcnt(0)
	s_barrier
	s_setprio 1
	v_mfma_f32_16x16x32_bf16 v[66:69], v[94:97], v[166:169], v[66:69]
	v_mfma_f32_16x16x32_bf16 v[62:65], v[110:113], v[166:169], v[62:65]
	v_mfma_f32_16x16x32_bf16 v[50:53], v[94:97], v[174:177], v[50:53]
	v_mfma_f32_16x16x32_bf16 v[46:49], v[110:113], v[174:177], v[46:49]
	v_mfma_f32_16x16x32_bf16 v[34:37], v[94:97], v[196:199], v[34:37]
	v_mfma_f32_16x16x32_bf16 v[30:33], v[110:113], v[196:199], v[30:33]
	v_mfma_f32_16x16x32_bf16 v[18:21], v[94:97], v[204:207], v[18:21]
	v_mfma_f32_16x16x32_bf16 v[14:17], v[110:113], v[204:207], v[14:17]
	v_mfma_f32_16x16x32_bf16 v[66:69], v[102:105], v[170:173], v[66:69]
	v_mfma_f32_16x16x32_bf16 v[62:65], v[114:117], v[170:173], v[62:65]
	v_mfma_f32_16x16x32_bf16 v[50:53], v[102:105], v[178:181], v[50:53]
	v_mfma_f32_16x16x32_bf16 v[46:49], v[114:117], v[178:181], v[46:49]
	v_mfma_f32_16x16x32_bf16 v[34:37], v[102:105], v[200:203], v[34:37]
	v_mfma_f32_16x16x32_bf16 v[30:33], v[114:117], v[200:203], v[30:33]
	v_mfma_f32_16x16x32_bf16 v[18:21], v[102:105], v[208:211], v[18:21]
	v_mfma_f32_16x16x32_bf16 v[14:17], v[114:117], v[208:211], v[14:17]
	v_mfma_f32_16x16x32_bf16 v[58:61], v[150:153], v[166:169], v[58:61]
	v_mfma_f32_16x16x32_bf16 v[54:57], v[158:161], v[166:169], v[54:57]
	v_mfma_f32_16x16x32_bf16 v[42:45], v[150:153], v[174:177], v[42:45]
	v_mfma_f32_16x16x32_bf16 v[38:41], v[158:161], v[174:177], v[38:41]
	v_mfma_f32_16x16x32_bf16 v[26:29], v[150:153], v[196:199], v[26:29]
	v_mfma_f32_16x16x32_bf16 v[22:25], v[158:161], v[196:199], v[22:25]
	v_mfma_f32_16x16x32_bf16 v[10:13], v[150:153], v[204:207], v[10:13]
	v_mfma_f32_16x16x32_bf16 v[6:9], v[158:161], v[204:207], v[6:9]
	v_mfma_f32_16x16x32_bf16 v[58:61], v[154:157], v[170:173], v[58:61]
	v_mfma_f32_16x16x32_bf16 v[54:57], v[162:165], v[170:173], v[54:57]
	v_mfma_f32_16x16x32_bf16 v[42:45], v[154:157], v[178:181], v[42:45]
	v_mfma_f32_16x16x32_bf16 v[38:41], v[162:165], v[178:181], v[38:41]
	v_mfma_f32_16x16x32_bf16 v[26:29], v[154:157], v[200:203], v[26:29]
	v_mfma_f32_16x16x32_bf16 v[22:25], v[162:165], v[200:203], v[22:25]
	v_mfma_f32_16x16x32_bf16 v[10:13], v[154:157], v[208:211], v[10:13]
	v_mfma_f32_16x16x32_bf16 v[6:9], v[162:165], v[208:211], v[6:9]
	s_setprio 0
	s_barrier
	s_add_i32 s45, 0, 0x18000
	s_add_u32 s26, s26, s42
	s_addc_u32 s27, s27, 0
	s_mov_b32 m0, s59
	s_nop 0
	global_load_lds_dwordx4 v182, s[26:27]
	s_mov_b32 m0, s62
	s_nop 0
	global_load_lds_dwordx4 v188, s[26:27]
	v_add_u32_e32 v114, s45, v217
	v_add_u32_e32 v162, 0x1c000, v217
	ds_read_b128 v[94:97], v114
	ds_read_b128 v[102:105], v114 offset:1024
	ds_read_b128 v[110:113], v114 offset:2048
	ds_read_b128 v[114:117], v114 offset:3072
	ds_read_b128 v[150:153], v162
	ds_read_b128 v[154:157], v162 offset:1024
	ds_read_b128 v[158:161], v162 offset:2048
	ds_read_b128 v[162:165], v162 offset:3072
	ds_read_b128 v[166:169], v236 offset:32768
	ds_read_b128 v[170:173], v236 offset:33792
	ds_read_b128 v[174:177], v236 offset:34816
	ds_read_b128 v[178:181], v236 offset:35840
	ds_read_b128 v[196:199], v236 offset:36864
	ds_read_b128 v[200:203], v236 offset:37888
	ds_read_b128 v[204:207], v236 offset:38912
	ds_read_b128 v[208:211], v236 offset:39936
	s_waitcnt vmcnt(8)
	s_waitcnt lgkmcnt(0)
	s_barrier
	s_setprio 1
	v_mfma_f32_16x16x32_bf16 v[146:149], v[94:97], v[166:169], v[146:149]
	v_mfma_f32_16x16x32_bf16 v[142:145], v[110:113], v[166:169], v[142:145]
	v_mfma_f32_16x16x32_bf16 v[130:133], v[94:97], v[174:177], v[130:133]
	v_mfma_f32_16x16x32_bf16 v[126:129], v[110:113], v[174:177], v[126:129]
	v_mfma_f32_16x16x32_bf16 v[106:109], v[94:97], v[196:199], v[106:109]
	v_mfma_f32_16x16x32_bf16 v[98:101], v[110:113], v[196:199], v[98:101]
	v_mfma_f32_16x16x32_bf16 v[82:85], v[94:97], v[204:207], v[82:85]
	v_mfma_f32_16x16x32_bf16 v[78:81], v[110:113], v[204:207], v[78:81]
	v_mfma_f32_16x16x32_bf16 v[146:149], v[102:105], v[170:173], v[146:149]
	v_mfma_f32_16x16x32_bf16 v[142:145], v[114:117], v[170:173], v[142:145]
	v_mfma_f32_16x16x32_bf16 v[130:133], v[102:105], v[178:181], v[130:133]
	v_mfma_f32_16x16x32_bf16 v[126:129], v[114:117], v[178:181], v[126:129]
	v_mfma_f32_16x16x32_bf16 v[106:109], v[102:105], v[200:203], v[106:109]
	v_mfma_f32_16x16x32_bf16 v[98:101], v[114:117], v[200:203], v[98:101]
	v_mfma_f32_16x16x32_bf16 v[82:85], v[102:105], v[208:211], v[82:85]
	v_mfma_f32_16x16x32_bf16 v[78:81], v[114:117], v[208:211], v[78:81]
	v_mfma_f32_16x16x32_bf16 v[138:141], v[150:153], v[166:169], v[138:141]
	v_mfma_f32_16x16x32_bf16 v[134:137], v[158:161], v[166:169], v[134:137]
	v_mfma_f32_16x16x32_bf16 v[122:125], v[150:153], v[174:177], v[122:125]
	v_mfma_f32_16x16x32_bf16 v[118:121], v[158:161], v[174:177], v[118:121]
	v_mfma_f32_16x16x32_bf16 v[90:93], v[150:153], v[196:199], v[90:93]
	v_mfma_f32_16x16x32_bf16 v[86:89], v[158:161], v[196:199], v[86:89]
	v_mfma_f32_16x16x32_bf16 v[74:77], v[150:153], v[204:207], v[74:77]
	v_mfma_f32_16x16x32_bf16 v[70:73], v[158:161], v[204:207], v[70:73]
	v_mfma_f32_16x16x32_bf16 v[138:141], v[154:157], v[170:173], v[138:141]
	v_mfma_f32_16x16x32_bf16 v[134:137], v[162:165], v[170:173], v[134:137]
	v_mfma_f32_16x16x32_bf16 v[122:125], v[154:157], v[178:181], v[122:125]
	v_mfma_f32_16x16x32_bf16 v[118:121], v[162:165], v[178:181], v[118:121]
	v_mfma_f32_16x16x32_bf16 v[90:93], v[154:157], v[200:203], v[90:93]
	v_mfma_f32_16x16x32_bf16 v[86:89], v[162:165], v[200:203], v[86:89]
	v_mfma_f32_16x16x32_bf16 v[74:77], v[154:157], v[208:211], v[74:77]
	v_mfma_f32_16x16x32_bf16 v[70:73], v[162:165], v[208:211], v[70:73]
	s_setprio 0
	s_barrier
	s_add_i32 s32, s45, s54
	s_mov_b32 m0, s32
	s_nop 0
	global_load_lds_dwordx4 v0, s[100:101]
	s_add_i32 m0, s32, 0x2000
	s_add_i32 s32, s54, 0x1c000
	global_load_lds_dwordx4 v190, s[100:101]
	s_add_u32 s70, s70, 0x80
	s_addc_u32 s71, s71, 0
	s_mov_b32 m0, s32
	s_add_i32 s32, s32, 0x2000
	global_load_lds_dwordx4 v0, s[70:71]
	s_mov_b32 m0, s32
	s_sub_u32 s26, s26, s42
	s_subb_u32 s27, s27, 0
	global_load_lds_dwordx4 v190, s[70:71]
	s_add_u32 s26, s26, 0x80
	s_addc_u32 s27, s27, 0
	s_mov_b32 m0, s63
	s_nop 0
	global_load_lds_dwordx4 v182, s[26:27]
	s_mov_b32 m0, s66
	s_nop 0
	global_load_lds_dwordx4 v188, s[26:27]
	ds_read_b128 v[166:169], v236 offset:49152
	ds_read_b128 v[170:173], v236 offset:50176
	ds_read_b128 v[174:177], v236 offset:51200
	ds_read_b128 v[178:181], v236 offset:52224
	ds_read_b128 v[196:199], v236 offset:53248
	ds_read_b128 v[200:203], v236 offset:54272
	ds_read_b128 v[204:207], v236 offset:55296
	ds_read_b128 v[208:211], v236 offset:56320
	s_waitcnt vmcnt(8)
	s_waitcnt lgkmcnt(0)
	s_barrier
	s_setprio 1
	v_mfma_f32_16x16x32_bf16 v[66:69], v[94:97], v[166:169], v[66:69]
	v_mfma_f32_16x16x32_bf16 v[62:65], v[110:113], v[166:169], v[62:65]
	v_mfma_f32_16x16x32_bf16 v[50:53], v[94:97], v[174:177], v[50:53]
	v_mfma_f32_16x16x32_bf16 v[46:49], v[110:113], v[174:177], v[46:49]
	v_mfma_f32_16x16x32_bf16 v[34:37], v[94:97], v[196:199], v[34:37]
	v_mfma_f32_16x16x32_bf16 v[30:33], v[110:113], v[196:199], v[30:33]
	v_mfma_f32_16x16x32_bf16 v[18:21], v[94:97], v[204:207], v[18:21]
	v_mfma_f32_16x16x32_bf16 v[14:17], v[110:113], v[204:207], v[14:17]
	v_mfma_f32_16x16x32_bf16 v[66:69], v[102:105], v[170:173], v[66:69]
	v_mfma_f32_16x16x32_bf16 v[62:65], v[114:117], v[170:173], v[62:65]
	v_mfma_f32_16x16x32_bf16 v[50:53], v[102:105], v[178:181], v[50:53]
	v_mfma_f32_16x16x32_bf16 v[46:49], v[114:117], v[178:181], v[46:49]
	v_mfma_f32_16x16x32_bf16 v[34:37], v[102:105], v[200:203], v[34:37]
	v_mfma_f32_16x16x32_bf16 v[30:33], v[114:117], v[200:203], v[30:33]
	v_mfma_f32_16x16x32_bf16 v[18:21], v[102:105], v[208:211], v[18:21]
	v_mfma_f32_16x16x32_bf16 v[14:17], v[114:117], v[208:211], v[14:17]
	v_mfma_f32_16x16x32_bf16 v[58:61], v[150:153], v[166:169], v[58:61]
	v_mfma_f32_16x16x32_bf16 v[54:57], v[158:161], v[166:169], v[54:57]
	v_mfma_f32_16x16x32_bf16 v[42:45], v[150:153], v[174:177], v[42:45]
	v_mfma_f32_16x16x32_bf16 v[38:41], v[158:161], v[174:177], v[38:41]
	v_mfma_f32_16x16x32_bf16 v[26:29], v[150:153], v[196:199], v[26:29]
	v_mfma_f32_16x16x32_bf16 v[22:25], v[158:161], v[196:199], v[22:25]
	v_mfma_f32_16x16x32_bf16 v[10:13], v[150:153], v[204:207], v[10:13]
	v_mfma_f32_16x16x32_bf16 v[6:9], v[158:161], v[204:207], v[6:9]
	v_mfma_f32_16x16x32_bf16 v[58:61], v[154:157], v[170:173], v[58:61]
	v_mfma_f32_16x16x32_bf16 v[54:57], v[162:165], v[170:173], v[54:57]
	v_mfma_f32_16x16x32_bf16 v[42:45], v[154:157], v[178:181], v[42:45]
	v_mfma_f32_16x16x32_bf16 v[38:41], v[162:165], v[178:181], v[38:41]
	v_mfma_f32_16x16x32_bf16 v[26:29], v[154:157], v[200:203], v[26:29]
	v_mfma_f32_16x16x32_bf16 v[22:25], v[162:165], v[200:203], v[22:25]
	v_mfma_f32_16x16x32_bf16 v[10:13], v[154:157], v[208:211], v[10:13]
	v_mfma_f32_16x16x32_bf16 v[6:9], v[162:165], v[208:211], v[6:9]
	s_setprio 0
	s_barrier
	s_add_u32 s10, s10, 0x100
	s_addc_u32 s11, s11, 0
	s_add_u32 s30, s30, 0x100
	s_addc_u32 s31, s31, 0
	s_cmp_ge_u32 s44, s67
	s_mov_b32 s26, s44
	s_cbranch_scc0 .LBB0_1065
	s_and_b64 vcc, exec, s[20:21]
	s_cbranch_vccnz .LBB0_1096
	s_mov_b64 s[30:31], 0
	s_andn2_b64 vcc, exec, s[22:23]
	s_mov_b64 s[26:27], 0
	s_cbranch_vccz .LBB0_1097
